# static s_setprio 1 for waves 4-7 over the GEMM phases, per-MFMA-block priority toggles removed
# baseline (speedup 1.0000x reference)
;     __device__ bool next(int i, Unit& u) const { const long L = (long)i * G + c; if (L >= hi) return false; unit_of((int)L, u); return true; }
; #define PG8_STAGE(bufoff, gbase) do { _Pragma("unroll") for (int _i = 0; _i < 2; ++_i) \
;         __builtin_amdgcn_global_load_lds((const unsigned*)((const char*)(gbase) + voffA[_i]), (LAS unsigned*)(lds + (bufoff) + ldsw + _i * 8192), 16, 0, 0); } while (0)
; #define PG8_WAIT_V(n) asm volatile("s_waitcnt vmcnt(" #n ")" ::: "memory")
; #define PG8_BAR __builtin_amdgcn_s_barrier()
; template <class Epi, bool SPLITA>
; __device__ __forceinline__ void gemm_phase(LAS unsigned char* lds, const Gemm g, const StaticOrder& S, const Epi& E) {
;     ...
;     Unit cur, nxt; int ui = 0;
;     if (!S.next(0, cur)) return;
;     E.prepare(lds, S, tid);
;     f32x4 acc[2][2][4][2];
; #pragma unroll
;     for (int a = 0; a < 2; ++a)
; #pragma unroll
;         for (int b = 0; b < 2; ++b)
; #pragma unroll
;             for (int m = 0; m < 4; ++m)
; #pragma unroll
;                 for (int n = 0; n < 2; ++n) acc[a][b][m][n] = (f32x4){0.f, 0.f, 0.f, 0.f};
;     f16x8 At[4][2], B0[2][2], B1[2][2];
;     const char* cB = (const char*)g.Bt + (size_t)cur.pn * tstep;
;     PG8_STAGE(PG8_SB(0, 0), cB); PG8_STAGE(PG8_SB(0, 1), cB + hstep); PG8_STAGE_A(PG8_SA(0, 0), cur.pm, 0, 0); PG8_STAGE_A(PG8_SA(0, 1), cur.pm, 0, 1);
;     if (wr == 1) PG8_BAR;
;     PG8_WAIT_V(2); PG8_BAR;
;     PG8_STAGE(PG8_SB(1, 0), cB + kstep); PG8_STAGE_A(PG8_SA(1, 0), cur.pm, 1, 0); PG8_STAGE(PG8_SB(1, 1), cB + hstep + kstep);
;     PG8_WAIT_V(6); PG8_BAR;
.LBB0_204:
	v_bfe_u32 v167, v76, 4, 2
	v_and_b32_e32 v163, 15, v76
	v_lshlrev_b32_e32 v16, 4, v167
	v_lshlrev_b32_e32 v17, 2, v76
	s_and_b32 s11, s4, 3
	v_lshl_or_b32 v16, v163, 6, v16
	s_lshl_b32 s6, s5, 13
	v_and_b32_e32 v17, 32, v17
	s_add_i32 m0, s8, 0x18000
	v_lshl_add_u64 v[8:9], v[8:9], 0, s[88:89]
	s_lshl_b32 s90, s5, 6
	v_bitop3_b32 v18, v16, s6, v17 bitop3:0xde
	s_lshl_b32 s6, s11, 12
	s_waitcnt vmcnt(2)
	s_barrier
	global_load_lds_dwordx4 v[8:9], off
	v_lshl_add_u64 v[6:7], v[6:7], 0, s[88:89]
	s_add_i32 m0, s8, 0x1a000
	s_add_i32 s91, s8, 0x8000
	s_add_i32 s92, s8, 0xa000
	v_bitop3_b32 v169, v16, s6, v17 bitop3:0xde
	global_load_lds_dwordx4 v[6:7], off
	v_lshl_add_u64 v[2:3], v[2:3], 0, s[88:89]
	s_mov_b32 m0, s91
	s_add_u32 s6, s0, 0x40080
	global_load_lds_dwordx4 v[2:3], off
	v_lshl_add_u64 v[2:3], v[4:5], 0, s[88:89]
	s_mov_b32 m0, s92
	s_addc_u32 s7, s1, 0
	global_load_lds_dwordx4 v[2:3], off
	s_add_i32 m0, s8, 0x1c000
	v_lshl_add_u64 v[2:3], s[6:7], 0, v[154:155]
	global_load_lds_dwordx4 v[2:3], off
	v_lshl_add_u64 v[2:3], s[6:7], 0, v[156:157]
	s_add_i32 m0, s8, 0x1e000
	s_lshl_b32 s5, s5, 7
	global_load_lds_dwordx4 v[2:3], off
	s_add_i32 s93, s5, 0
	s_add_i32 s93, s93, 0x26100
	s_cmpk_lt_u32 s10, 0x100
	s_cselect_b64 s[34:35], -1, 0
	s_cmp_lt_u32 s11, 2
	s_cselect_b64 s[76:77], -1, 0
	s_lshl_b32 s5, s4, 3
	s_bfe_u32 s64, s4, 0x10001
	s_and_b32 s36, s5, 8
	s_or_b32 s65, s64, -10
	s_lshl_b32 s85, s11, 6
	s_lshl_b32 s4, s11, 7
	v_lshlrev_b32_e32 v2, 14, v10
	s_add_u32 s46, s20, s4
	v_and_b32_e32 v2, 0xffff8000, v2
	s_addc_u32 s14, s21, 0
	v_lshl_add_u32 v2, v11, 11, v2
	v_and_b32_e32 v3, 1, v10
	s_add_u32 s80, s40, s4
	v_lshl_or_b32 v2, v3, 6, v2
	s_addc_u32 s81, s41, 0
	v_lshl_add_u32 v194, v13, 1, v2
	v_lshlrev_b32_e32 v2, 14, v12
	s_add_u32 s15, s22, s4
	v_readlane_b32 s6, v254, 39
	v_and_b32_e32 v2, 0xffff8000, v2
	s_mov_b32 s4, s52
	v_readlane_b32 s7, v254, 40
	v_lshl_add_u32 v2, v14, 11, v2
	v_and_b32_e32 v3, 1, v12
	v_writelane_b32 v254, s4, 27
	s_waitcnt vmcnt(6)
	v_lshl_or_b32 v2, v3, 6, v2
	v_lshl_add_u64 v[158:159], s[6:7], 0, v[194:195]
	v_writelane_b32 v254, s5, 28
	s_mov_b32 s4, s70
	v_lshl_add_u32 v194, v15, 1, v2
	v_mov_b32_e32 v2, 0
	v_writelane_b32 v254, s4, 25
	s_addc_u32 s12, s23, 0
	s_mov_b32 s33, 0
	v_add_u32_e32 v171, 0, v18
	s_mov_b32 s13, s52
	v_writelane_b32 v254, s5, 26
	v_mov_b32_e32 v3, v2
	v_mov_b32_e32 v4, v2
	v_mov_b32_e32 v5, v2
	v_mov_b32_e32 v6, v2
	v_mov_b32_e32 v7, v2
	v_mov_b32_e32 v8, v2
	v_mov_b32_e32 v9, v2
	v_mov_b32_e32 v10, v2
	v_mov_b32_e32 v11, v2
	v_mov_b32_e32 v12, v2
	v_mov_b32_e32 v13, v2
	v_mov_b32_e32 v14, v2
	v_mov_b32_e32 v15, v2
	v_mov_b32_e32 v16, v2
	v_mov_b32_e32 v17, v2
	v_mov_b32_e32 v18, v2
	v_mov_b32_e32 v19, v2
	v_mov_b32_e32 v20, v2
	v_mov_b32_e32 v21, v2
	v_mov_b32_e32 v22, v2
	v_mov_b32_e32 v23, v2
	v_mov_b32_e32 v24, v2
	v_mov_b32_e32 v25, v2
	v_mov_b32_e32 v26, v2
	v_mov_b32_e32 v27, v2
	v_mov_b32_e32 v28, v2
	v_mov_b32_e32 v29, v2
	v_mov_b32_e32 v30, v2
	v_mov_b32_e32 v31, v2
	v_mov_b32_e32 v32, v2
	v_mov_b32_e32 v33, v2
	v_mov_b32_e32 v34, v2
	v_mov_b32_e32 v35, v2
	v_mov_b32_e32 v36, v2
	v_mov_b32_e32 v37, v2
	v_mov_b32_e32 v38, v2
	v_mov_b32_e32 v39, v2
	v_mov_b32_e32 v40, v2
	v_mov_b32_e32 v41, v2
	v_mov_b32_e32 v42, v2
	v_mov_b32_e32 v43, v2
	v_mov_b32_e32 v44, v2
	v_mov_b32_e32 v45, v2
	v_mov_b32_e32 v46, v2
	v_mov_b32_e32 v47, v2
	v_mov_b32_e32 v48, v2
	v_mov_b32_e32 v49, v2
	v_mov_b32_e32 v50, v2
	v_mov_b32_e32 v51, v2
	v_mov_b32_e32 v52, v2
	v_mov_b32_e32 v53, v2
	v_mov_b32_e32 v54, v2
	v_mov_b32_e32 v55, v2
	v_mov_b32_e32 v56, v2
	v_mov_b32_e32 v57, v2
	v_mov_b32_e32 v58, v2
	v_mov_b32_e32 v59, v2
	v_mov_b32_e32 v60, v2
	v_mov_b32_e32 v61, v2
	v_mov_b32_e32 v62, v2
	v_mov_b32_e32 v63, v2
	v_mov_b32_e32 v64, v2
	v_mov_b32_e32 v65, v2
	v_mov_b32_e32 v66, v2
	v_mov_b32_e32 v67, v2
	v_mov_b32_e32 v68, v2
	v_mov_b32_e32 v69, v2
	v_mov_b32_e32 v70, v2
	v_mov_b32_e32 v71, v2
	v_mov_b32_e32 v72, v2
	v_mov_b32_e32 v73, v2
	v_mov_b32_e32 v74, v2
	v_mov_b32_e32 v75, v2
	v_mov_b32_e32 v76, v2
	v_mov_b32_e32 v77, v2
	v_mov_b32_e32 v78, v2
	v_mov_b32_e32 v79, v2
	v_mov_b32_e32 v80, v2
	v_mov_b32_e32 v81, v2
	v_mov_b32_e32 v82, v2
	v_mov_b32_e32 v83, v2
	v_mov_b32_e32 v84, v2
	v_mov_b32_e32 v85, v2
	v_mov_b32_e32 v86, v2
	v_mov_b32_e32 v87, v2
	v_mov_b32_e32 v88, v2
	v_mov_b32_e32 v89, v2
	v_mov_b32_e32 v90, v2
	v_mov_b32_e32 v91, v2
	v_mov_b32_e32 v92, v2
	v_mov_b32_e32 v93, v2
	v_mov_b32_e32 v94, v2
	v_mov_b32_e32 v95, v2
	v_mov_b32_e32 v96, v2
	v_mov_b32_e32 v97, v2
	v_mov_b32_e32 v98, v2
	v_mov_b32_e32 v99, v2
	v_mov_b32_e32 v100, v2
	v_mov_b32_e32 v101, v2
	v_mov_b32_e32 v102, v2
	v_mov_b32_e32 v103, v2
	v_mov_b32_e32 v104, v2
	v_mov_b32_e32 v105, v2
	v_mov_b32_e32 v106, v2
	v_mov_b32_e32 v107, v2
	v_mov_b32_e32 v108, v2
	v_mov_b32_e32 v109, v2
	v_mov_b32_e32 v110, v2
	v_mov_b32_e32 v111, v2
	v_mov_b32_e32 v112, v2
	v_mov_b32_e32 v113, v2
	v_mov_b32_e32 v114, v2
	v_mov_b32_e32 v115, v2
	v_mov_b32_e32 v116, v2
	v_mov_b32_e32 v117, v2
	v_mov_b32_e32 v118, v2
	v_mov_b32_e32 v119, v2
	v_mov_b32_e32 v120, v2
	v_mov_b32_e32 v121, v2
	v_mov_b32_e32 v122, v2
	v_mov_b32_e32 v123, v2
	v_mov_b32_e32 v124, v2
	v_mov_b32_e32 v125, v2
	v_mov_b32_e32 v126, v2
	v_mov_b32_e32 v127, v2
	v_mov_b32_e32 v128, v2
	v_mov_b32_e32 v129, v2
	v_lshl_add_u64 v[160:161], s[6:7], 0, v[194:195]
	s_barrier
	v_readfirstlane_b32 s100, v0
	s_nop 3
	s_cmp_ge_u32 s100, 0x100
	s_cbranch_scc0 .Lprio_skip1
	s_setprio 1
; #define PG8_BAR __builtin_amdgcn_s_barrier()
; template <class Epi, bool SPLITA>
; __device__ __forceinline__ void gemm_phase(LAS unsigned char* lds, const Gemm g, const StaticOrder& S, const Epi& E) {
;     ...
;         if (wr == 0) PG8_BAR;
;         E(acc, cur, ui, lds, wr, wc, fr, fq);
;         if (!has_next) break;
; #pragma unroll
;         for (int a = 0; a < 2; ++a)
; #pragma unroll
;             for (int b = 0; b < 2; ++b)
; #pragma unroll
;                 for (int m = 0; m < 4; ++m)
; #pragma unroll
;                     for (int n = 0; n < 2; ++n) acc[a][b][m][n] = (f32x4){0.f, 0.f, 0.f, 0.f};
;         cur = nxt; cB = nB; ++ui;
;         if (wr == 1) PG8_BAR;
;     }
.Lprio_skip1:
	s_branch .LBB0_206
.LBB0_205:
	v_mov_b32_e32 v2, 0
	s_mov_b32 s13, s66
	s_mov_b32 s70, s86
	v_mov_b32_e32 v3, v2
	v_mov_b32_e32 v4, v2
	v_mov_b32_e32 v5, v2
	v_mov_b32_e32 v6, v2
	v_mov_b32_e32 v7, v2
	v_mov_b32_e32 v8, v2
	v_mov_b32_e32 v9, v2
	v_mov_b32_e32 v10, v2
	v_mov_b32_e32 v11, v2
	v_mov_b32_e32 v12, v2
	v_mov_b32_e32 v13, v2
	v_mov_b32_e32 v14, v2
	v_mov_b32_e32 v15, v2
	v_mov_b32_e32 v16, v2
	v_mov_b32_e32 v17, v2
	v_mov_b32_e32 v18, v2
	v_mov_b32_e32 v19, v2
	v_mov_b32_e32 v20, v2
	v_mov_b32_e32 v21, v2
	v_mov_b32_e32 v22, v2
	v_mov_b32_e32 v23, v2
	v_mov_b32_e32 v24, v2
	v_mov_b32_e32 v25, v2
	v_mov_b32_e32 v26, v2
	v_mov_b32_e32 v27, v2
	v_mov_b32_e32 v28, v2
	v_mov_b32_e32 v29, v2
	v_mov_b32_e32 v30, v2
	v_mov_b32_e32 v31, v2
	v_mov_b32_e32 v32, v2
	v_mov_b32_e32 v33, v2
	v_mov_b32_e32 v34, v2
	v_mov_b32_e32 v35, v2
	v_mov_b32_e32 v36, v2
	v_mov_b32_e32 v37, v2
	v_mov_b32_e32 v38, v2
	v_mov_b32_e32 v39, v2
	v_mov_b32_e32 v40, v2
	v_mov_b32_e32 v41, v2
	v_mov_b32_e32 v42, v2
	v_mov_b32_e32 v43, v2
	v_mov_b32_e32 v44, v2
	v_mov_b32_e32 v45, v2
	v_mov_b32_e32 v46, v2
	v_mov_b32_e32 v47, v2
	v_mov_b32_e32 v48, v2
	v_mov_b32_e32 v49, v2
	v_mov_b32_e32 v50, v2
	v_mov_b32_e32 v51, v2
	v_mov_b32_e32 v52, v2
	v_mov_b32_e32 v53, v2
	v_mov_b32_e32 v54, v2
	v_mov_b32_e32 v55, v2
	v_mov_b32_e32 v56, v2
	v_mov_b32_e32 v57, v2
	v_mov_b32_e32 v58, v2
	v_mov_b32_e32 v59, v2
	v_mov_b32_e32 v60, v2
	v_mov_b32_e32 v61, v2
	v_mov_b32_e32 v62, v2
	v_mov_b32_e32 v63, v2
	v_mov_b32_e32 v64, v2
	v_mov_b32_e32 v65, v2
	v_mov_b32_e32 v66, v2
	v_mov_b32_e32 v67, v2
	v_mov_b32_e32 v68, v2
	v_mov_b32_e32 v69, v2
	v_mov_b32_e32 v70, v2
	v_mov_b32_e32 v71, v2
	v_mov_b32_e32 v72, v2
	v_mov_b32_e32 v73, v2
	v_mov_b32_e32 v74, v2
	v_mov_b32_e32 v75, v2
	v_mov_b32_e32 v76, v2
	v_mov_b32_e32 v77, v2
	v_mov_b32_e32 v78, v2
	v_mov_b32_e32 v79, v2
	v_mov_b32_e32 v80, v2
	v_mov_b32_e32 v81, v2
	v_mov_b32_e32 v82, v2
	v_mov_b32_e32 v83, v2
	v_mov_b32_e32 v84, v2
	v_mov_b32_e32 v85, v2
	v_mov_b32_e32 v86, v2
	v_mov_b32_e32 v87, v2
	v_mov_b32_e32 v88, v2
	v_mov_b32_e32 v89, v2
	v_mov_b32_e32 v90, v2
	v_mov_b32_e32 v91, v2
	v_mov_b32_e32 v92, v2
	v_mov_b32_e32 v93, v2
	v_mov_b32_e32 v94, v2
	v_mov_b32_e32 v95, v2
	v_mov_b32_e32 v96, v2
	v_mov_b32_e32 v97, v2
	v_mov_b32_e32 v98, v2
	v_mov_b32_e32 v99, v2
	v_mov_b32_e32 v100, v2
	v_mov_b32_e32 v101, v2
	v_mov_b32_e32 v102, v2
	v_mov_b32_e32 v103, v2
	v_mov_b32_e32 v104, v2
	v_mov_b32_e32 v105, v2
	v_mov_b32_e32 v106, v2
	v_mov_b32_e32 v107, v2
	v_mov_b32_e32 v108, v2
	v_mov_b32_e32 v109, v2
	v_mov_b32_e32 v110, v2
	v_mov_b32_e32 v111, v2
	v_mov_b32_e32 v112, v2
	v_mov_b32_e32 v113, v2
	v_mov_b32_e32 v114, v2
	v_mov_b32_e32 v115, v2
	v_mov_b32_e32 v116, v2
	v_mov_b32_e32 v117, v2
	v_mov_b32_e32 v118, v2
	v_mov_b32_e32 v119, v2
	v_mov_b32_e32 v120, v2
	v_mov_b32_e32 v121, v2
	v_mov_b32_e32 v122, v2
	v_mov_b32_e32 v123, v2
	v_mov_b32_e32 v124, v2
	v_mov_b32_e32 v125, v2
	v_mov_b32_e32 v126, v2
	v_mov_b32_e32 v127, v2
	v_mov_b32_e32 v128, v2
	v_mov_b32_e32 v129, v2
	s_mov_b32 s33, s87
	s_andn2_b64 vcc, exec, s[4:5]
	s_mov_b64 s[0:1], s[68:69]
	s_cbranch_vccz .LBB0_316

; #define PG8_STAGE(bufoff, gbase) do { _Pragma("unroll") for (int _i = 0; _i < 2; ++_i) \
;         __builtin_amdgcn_global_load_lds((const unsigned*)((const char*)(gbase) + voffA[_i]), (LAS unsigned*)(lds + (bufoff) + ldsw + _i * 8192), 16, 0, 0); } while (0)
; #define PG8_LDA(dst, b, h) do { _Pragma("unroll") for (int m = 0; m < 4; ++m) _Pragma("unroll") for (int k = 0; k < 2; ++k) dst[m][k] = *(const LAS f16x8*)(lds + PG8_SA(b, h) + aoff + m * 2048 + k * 1024); } while (0)
; #define PG8_LDB(dst, b, h) do { _Pragma("unroll") for (int n = 0; n < 2; ++n) _Pragma("unroll") for (int k = 0; k < 2; ++k) dst[n][k] = *(const LAS f16x8*)(lds + PG8_SB(b, h) + boff + n * 2048 + k * 1024); } while (0)
; #define PG8_MMA(ai, bj, At, Bt) do { __builtin_amdgcn_s_setprio(1); _Pragma("unroll") for (int m = 0; m < 4; ++m) _Pragma("unroll") for (int n = 0; n < 2; ++n) _Pragma("unroll") for (int k = 0; k < 2; ++k) \
;         acc[ai][bj][m][n] = __builtin_amdgcn_mfma_f32_16x16x32_f16(Bt[n][k], At[m][k], acc[ai][bj][m][n], 0, 0, 0); __builtin_amdgcn_s_setprio(0); } while (0)
; #define PG8_WAIT_V(n) asm volatile("s_waitcnt vmcnt(" #n ")" ::: "memory")
; #define PG8_WAIT_L(n) asm volatile("s_waitcnt lgkmcnt(" #n ")" ::: "memory")
; #define PG8_BAR __builtin_amdgcn_s_barrier()
; #define PG8_SCHED __builtin_amdgcn_sched_barrier(0)
; template <class Epi, bool SPLITA>
; __device__ __forceinline__ void gemm_phase(LAS unsigned char* lds, const Gemm g, const StaticOrder& S, const Epi& E) {
;     ...
;             PG8_LDB(B0, 0, 0); PG8_LDB(B1, 0, 1); PG8_SCHED; PG8_LDA(At, 0, 0); PG8_STAGE_A(PG8_SA(1, 1), cur.pm, t + 1, 1);
;             PG8_WAIT_V(8); PG8_WAIT_L(0); PG8_BAR; PG8_MMA(0, 0, At, B0); PG8_MMA(0, 1, At, B1); PG8_BAR; PG8_SCHED;
;             PG8_LDA(At, 0, 1); PG8_STAGE(PG8_SB(0, 0), b2); PG8_STAGE(PG8_SB(0, 1), b2 + hstep); PG8_STAGE_A(PG8_SA(0, 0), pm2, kt2, 0);
;             PG8_WAIT_V(8); PG8_WAIT_L(0); PG8_BAR; PG8_MMA(1, 0, At, B0); PG8_MMA(1, 1, At, B1); PG8_BAR; PG8_SCHED;
.LBB0_209:
	s_add_u32 s10, s0, 0x100
	s_addc_u32 s11, s1, 0
	s_add_u32 s72, s52, s0
	s_addc_u32 s73, s53, s1
	s_add_i32 s82, 0, 0x10000
	s_add_i32 s83, 0, 0x14000
	v_add_u32_e32 v146, s82, v169
	v_add_u32_e32 v162, s83, v169
	ds_read_b128 v[134:137], v146
	ds_read_b128 v[138:141], v146 offset:1024
	ds_read_b128 v[142:145], v146 offset:2048
	ds_read_b128 v[146:149], v146 offset:3072
	ds_read_b128 v[150:153], v162
	ds_read_b128 v[172:175], v162 offset:1024
	ds_read_b128 v[176:179], v162 offset:2048
	ds_read_b128 v[180:183], v162 offset:3072
	s_add_i32 vcc_hi, s82, s95
	s_add_i32 m0, s8, 0xc000
	s_add_i32 vcc_lo, s8, 0xe000
	s_add_i32 s74, vcc_hi, 0x2000
	s_cmpk_eq_i32 s0, 0x700
	s_cselect_b32 s73, s67, s73
	s_cselect_b32 s72, s79, s72
	s_cselect_b32 s82, s78, s70
	v_lshl_add_u64 v[164:165], v[130:131], 0, s[0:1]
	ds_read_b128 v[184:187], v171
	ds_read_b128 v[188:191], v171 offset:1024
	ds_read_b128 v[200:203], v171 offset:2048
	ds_read_b128 v[204:207], v171 offset:3072
	ds_read_b128 v[208:211], v171 offset:4096
	ds_read_b128 v[212:215], v171 offset:5120
	ds_read_b128 v[216:219], v171 offset:6144
	ds_read_b128 v[230:233], v171 offset:7168
	global_load_lds_dwordx4 v[164:165], off
	v_lshl_add_u64 v[164:165], v[132:133], 0, s[0:1]
	s_mov_b32 m0, vcc_lo
	s_nop 0
	global_load_lds_dwordx4 v[164:165], off
	s_waitcnt vmcnt(8)
	s_waitcnt lgkmcnt(0)
	s_barrier
	s_waitcnt lgkmcnt(0)
	v_mfma_f32_16x16x32_f16 v[126:129], v[134:137], v[184:187], v[126:129]
	v_mfma_f32_16x16x32_f16 v[122:125], v[142:145], v[184:187], v[122:125]
	v_mfma_f32_16x16x32_f16 v[118:121], v[134:137], v[200:203], v[118:121]
	v_mfma_f32_16x16x32_f16 v[114:117], v[142:145], v[200:203], v[114:117]
	v_mfma_f32_16x16x32_f16 v[110:113], v[134:137], v[208:211], v[110:113]
	v_mfma_f32_16x16x32_f16 v[106:109], v[142:145], v[208:211], v[106:109]
	v_mfma_f32_16x16x32_f16 v[102:105], v[134:137], v[216:219], v[102:105]
	v_mfma_f32_16x16x32_f16 v[98:101], v[142:145], v[216:219], v[98:101]
	v_mfma_f32_16x16x32_f16 v[126:129], v[138:141], v[188:191], v[126:129]
	v_mfma_f32_16x16x32_f16 v[122:125], v[146:149], v[188:191], v[122:125]
	v_mfma_f32_16x16x32_f16 v[118:121], v[138:141], v[204:207], v[118:121]
	v_mfma_f32_16x16x32_f16 v[114:117], v[146:149], v[204:207], v[114:117]
	v_mfma_f32_16x16x32_f16 v[110:113], v[138:141], v[212:215], v[110:113]
	v_mfma_f32_16x16x32_f16 v[106:109], v[146:149], v[212:215], v[106:109]
	v_mfma_f32_16x16x32_f16 v[102:105], v[138:141], v[230:233], v[102:105]
	v_mfma_f32_16x16x32_f16 v[98:101], v[146:149], v[230:233], v[98:101]
	v_mfma_f32_16x16x32_f16 v[94:97], v[150:153], v[184:187], v[94:97]
	v_mfma_f32_16x16x32_f16 v[90:93], v[176:179], v[184:187], v[90:93]
	v_mfma_f32_16x16x32_f16 v[86:89], v[150:153], v[200:203], v[86:89]
	v_mfma_f32_16x16x32_f16 v[82:85], v[176:179], v[200:203], v[82:85]
	v_mfma_f32_16x16x32_f16 v[78:81], v[150:153], v[208:211], v[78:81]
	v_mfma_f32_16x16x32_f16 v[74:77], v[176:179], v[208:211], v[74:77]
	v_mfma_f32_16x16x32_f16 v[70:73], v[150:153], v[216:219], v[70:73]
	v_mfma_f32_16x16x32_f16 v[66:69], v[176:179], v[216:219], v[66:69]
	v_mfma_f32_16x16x32_f16 v[94:97], v[172:175], v[188:191], v[94:97]
	v_mfma_f32_16x16x32_f16 v[90:93], v[180:183], v[188:191], v[90:93]
	v_mfma_f32_16x16x32_f16 v[86:89], v[172:175], v[204:207], v[86:89]
	v_mfma_f32_16x16x32_f16 v[82:85], v[180:183], v[204:207], v[82:85]
	v_mfma_f32_16x16x32_f16 v[78:81], v[172:175], v[212:215], v[78:81]
	v_mfma_f32_16x16x32_f16 v[74:77], v[180:183], v[212:215], v[74:77]
	v_mfma_f32_16x16x32_f16 v[70:73], v[172:175], v[230:233], v[70:73]
	v_mfma_f32_16x16x32_f16 v[66:69], v[180:183], v[230:233], v[66:69]
	s_barrier
	s_mov_b32 m0, vcc_hi
	v_lshl_add_u64 v[164:165], s[72:73], 0, v[154:155]
	ds_read_b128 v[184:187], v171 offset:16384
	ds_read_b128 v[188:191], v171 offset:17408
	ds_read_b128 v[200:203], v171 offset:18432
	ds_read_b128 v[204:207], v171 offset:19456
	ds_read_b128 v[208:211], v171 offset:20480
	ds_read_b128 v[212:215], v171 offset:21504
	ds_read_b128 v[216:219], v171 offset:22528
	ds_read_b128 v[230:233], v171 offset:23552
	global_load_lds_dwordx4 v[164:165], off
	s_mov_b32 m0, s74
	s_cselect_b32 s74, 0, s10
	s_add_u32 s0, s72, 0x40000
	v_lshl_add_u64 v[192:193], s[72:73], 0, v[156:157]
	s_addc_u32 s1, s73, 0
	s_add_i32 s75, s83, s95
	global_load_lds_dwordx4 v[192:193], off
	v_lshl_add_u64 v[220:221], s[0:1], 0, v[154:155]
	s_mov_b32 m0, s75
	s_ashr_i32 s83, s82, 31
	global_load_lds_dwordx4 v[220:221], off
	v_lshl_add_u64 v[220:221], s[0:1], 0, v[156:157]
	s_add_i32 m0, s75, 0x2000
	s_lshl_b64 s[0:1], s[82:83], 19
	s_add_u32 s0, s40, s0
	s_addc_u32 s1, s41, s1
	s_add_u32 s0, s0, s74
	s_addc_u32 s1, s1, 0
	global_load_lds_dwordx4 v[220:221], off
	v_lshl_add_u64 v[220:221], s[0:1], 0, v[154:155]
	s_mov_b32 m0, s8
	v_lshl_add_u64 v[234:235], s[0:1], 0, v[156:157]
	global_load_lds_dwordx4 v[220:221], off
	s_mov_b32 m0, s9
	s_nop 0
	global_load_lds_dwordx4 v[234:235], off
	s_waitcnt vmcnt(8)
	s_waitcnt lgkmcnt(0)
	s_barrier
; #define PG8_STAGE(bufoff, gbase) do { _Pragma("unroll") for (int _i = 0; _i < 2; ++_i) \
;         __builtin_amdgcn_global_load_lds((const unsigned*)((const char*)(gbase) + voffA[_i]), (LAS unsigned*)(lds + (bufoff) + ldsw + _i * 8192), 16, 0, 0); } while (0)
; #define PG8_LDA(dst, b, h) do { _Pragma("unroll") for (int m = 0; m < 4; ++m) _Pragma("unroll") for (int k = 0; k < 2; ++k) dst[m][k] = *(const LAS f16x8*)(lds + PG8_SA(b, h) + aoff + m * 2048 + k * 1024); } while (0)
; #define PG8_LDB(dst, b, h) do { _Pragma("unroll") for (int n = 0; n < 2; ++n) _Pragma("unroll") for (int k = 0; k < 2; ++k) dst[n][k] = *(const LAS f16x8*)(lds + PG8_SB(b, h) + boff + n * 2048 + k * 1024); } while (0)
; #define PG8_MMA(ai, bj, At, Bt) do { __builtin_amdgcn_s_setprio(1); _Pragma("unroll") for (int m = 0; m < 4; ++m) _Pragma("unroll") for (int n = 0; n < 2; ++n) _Pragma("unroll") for (int k = 0; k < 2; ++k) \
;         acc[ai][bj][m][n] = __builtin_amdgcn_mfma_f32_16x16x32_f16(Bt[n][k], At[m][k], acc[ai][bj][m][n], 0, 0, 0); __builtin_amdgcn_s_setprio(0); } while (0)
; #define PG8_WAIT_V(n) asm volatile("s_waitcnt vmcnt(" #n ")" ::: "memory")
; #define PG8_WAIT_L(n) asm volatile("s_waitcnt lgkmcnt(" #n ")" ::: "memory")
; #define PG8_BAR __builtin_amdgcn_s_barrier()
; #define PG8_SCHED __builtin_amdgcn_sched_barrier(0)
; template <class Epi, bool SPLITA>
; __device__ __forceinline__ void gemm_phase(LAS unsigned char* lds, const Gemm g, const StaticOrder& S, const Epi& E) {
;     ...
;             PG8_WAIT_V(8); PG8_WAIT_L(0); PG8_BAR; PG8_MMA(1, 0, At, B0); PG8_MMA(1, 1, At, B1); PG8_BAR; PG8_SCHED;
;             PG8_LDB(B0, 1, 0); PG8_LDB(B1, 1, 1); PG8_SCHED; PG8_LDA(At, 1, 0); PG8_STAGE_A(PG8_SA(0, 1), pm2, kt2, 1);
;             PG8_WAIT_V(8); PG8_WAIT_L(0); PG8_BAR; PG8_MMA(0, 0, At, B0); PG8_MMA(0, 1, At, B1); PG8_BAR; PG8_SCHED;
;             PG8_LDA(At, 1, 1); PG8_STAGE(PG8_SB(1, 0), b3); PG8_STAGE(PG8_SB(1, 1), b3 + hstep); PG8_STAGE_A(PG8_SA(1, 0), pm2, kt2 + 1, 0);
	s_waitcnt lgkmcnt(0)
	v_mfma_f32_16x16x32_f16 v[62:65], v[134:137], v[184:187], v[62:65]
	v_mfma_f32_16x16x32_f16 v[58:61], v[142:145], v[184:187], v[58:61]
	v_mfma_f32_16x16x32_f16 v[54:57], v[134:137], v[200:203], v[54:57]
	v_mfma_f32_16x16x32_f16 v[50:53], v[142:145], v[200:203], v[50:53]
	v_mfma_f32_16x16x32_f16 v[46:49], v[134:137], v[208:211], v[46:49]
	v_mfma_f32_16x16x32_f16 v[42:45], v[142:145], v[208:211], v[42:45]
	v_mfma_f32_16x16x32_f16 v[38:41], v[134:137], v[216:219], v[38:41]
	v_mfma_f32_16x16x32_f16 v[34:37], v[142:145], v[216:219], v[34:37]
	v_mfma_f32_16x16x32_f16 v[62:65], v[138:141], v[188:191], v[62:65]
	v_mfma_f32_16x16x32_f16 v[58:61], v[146:149], v[188:191], v[58:61]
	v_mfma_f32_16x16x32_f16 v[54:57], v[138:141], v[204:207], v[54:57]
	v_mfma_f32_16x16x32_f16 v[50:53], v[146:149], v[204:207], v[50:53]
	v_mfma_f32_16x16x32_f16 v[46:49], v[138:141], v[212:215], v[46:49]
	v_mfma_f32_16x16x32_f16 v[42:45], v[146:149], v[212:215], v[42:45]
	v_mfma_f32_16x16x32_f16 v[38:41], v[138:141], v[230:233], v[38:41]
	v_mfma_f32_16x16x32_f16 v[34:37], v[146:149], v[230:233], v[34:37]
	v_mfma_f32_16x16x32_f16 v[30:33], v[150:153], v[184:187], v[30:33]
	v_mfma_f32_16x16x32_f16 v[26:29], v[176:179], v[184:187], v[26:29]
	v_mfma_f32_16x16x32_f16 v[22:25], v[150:153], v[200:203], v[22:25]
	v_mfma_f32_16x16x32_f16 v[18:21], v[176:179], v[200:203], v[18:21]
	v_mfma_f32_16x16x32_f16 v[14:17], v[150:153], v[208:211], v[14:17]
	v_mfma_f32_16x16x32_f16 v[10:13], v[176:179], v[208:211], v[10:13]
	v_mfma_f32_16x16x32_f16 v[6:9], v[150:153], v[216:219], v[6:9]
	v_mfma_f32_16x16x32_f16 v[2:5], v[176:179], v[216:219], v[2:5]
	v_mfma_f32_16x16x32_f16 v[30:33], v[172:175], v[188:191], v[30:33]
	v_mfma_f32_16x16x32_f16 v[26:29], v[180:183], v[188:191], v[26:29]
	v_mfma_f32_16x16x32_f16 v[22:25], v[172:175], v[204:207], v[22:25]
	v_mfma_f32_16x16x32_f16 v[18:21], v[180:183], v[204:207], v[18:21]
	v_mfma_f32_16x16x32_f16 v[14:17], v[172:175], v[212:215], v[14:17]
	v_mfma_f32_16x16x32_f16 v[10:13], v[180:183], v[212:215], v[10:13]
	v_mfma_f32_16x16x32_f16 v[6:9], v[172:175], v[230:233], v[6:9]
	v_mfma_f32_16x16x32_f16 v[2:5], v[180:183], v[230:233], v[2:5]
	s_barrier
	s_add_i32 s74, 0, 0x18000
	s_add_i32 s75, 0, 0x1c000
	v_add_u32_e32 v146, s74, v169
	v_add_u32_e32 v162, s75, v169
	ds_read_b128 v[134:137], v146
	ds_read_b128 v[138:141], v146 offset:1024
	ds_read_b128 v[142:145], v146 offset:2048
	ds_read_b128 v[146:149], v146 offset:3072
	ds_read_b128 v[150:153], v162
	ds_read_b128 v[172:175], v162 offset:1024
	ds_read_b128 v[176:179], v162 offset:2048
	ds_read_b128 v[180:183], v162 offset:3072
	s_add_u32 s0, s0, 0x40000
	s_addc_u32 s1, s1, 0
	s_mov_b32 m0, s37
	v_lshl_add_u64 v[236:237], s[0:1], 0, v[154:155]
	ds_read_b128 v[184:187], v171 offset:32768
	ds_read_b128 v[188:191], v171 offset:33792
	ds_read_b128 v[200:203], v171 offset:34816
	ds_read_b128 v[204:207], v171 offset:35840
	ds_read_b128 v[208:211], v171 offset:36864
	ds_read_b128 v[212:215], v171 offset:37888
	ds_read_b128 v[216:219], v171 offset:38912
	ds_read_b128 v[230:233], v171 offset:39936
	global_load_lds_dwordx4 v[236:237], off
	v_lshl_add_u64 v[236:237], s[0:1], 0, v[156:157]
	s_mov_b32 m0, s31
	s_nop 0
	global_load_lds_dwordx4 v[236:237], off
	s_waitcnt vmcnt(8)
	s_waitcnt lgkmcnt(0)
	s_barrier
	s_waitcnt lgkmcnt(0)
	v_mfma_f32_16x16x32_f16 v[126:129], v[134:137], v[184:187], v[126:129]
	v_mfma_f32_16x16x32_f16 v[122:125], v[142:145], v[184:187], v[122:125]
	v_mfma_f32_16x16x32_f16 v[118:121], v[134:137], v[200:203], v[118:121]
	v_mfma_f32_16x16x32_f16 v[114:117], v[142:145], v[200:203], v[114:117]
	v_mfma_f32_16x16x32_f16 v[110:113], v[134:137], v[208:211], v[110:113]
	v_mfma_f32_16x16x32_f16 v[106:109], v[142:145], v[208:211], v[106:109]
	v_mfma_f32_16x16x32_f16 v[102:105], v[134:137], v[216:219], v[102:105]
	v_mfma_f32_16x16x32_f16 v[98:101], v[142:145], v[216:219], v[98:101]
	v_mfma_f32_16x16x32_f16 v[126:129], v[138:141], v[188:191], v[126:129]
	v_mfma_f32_16x16x32_f16 v[122:125], v[146:149], v[188:191], v[122:125]
	v_mfma_f32_16x16x32_f16 v[118:121], v[138:141], v[204:207], v[118:121]
	v_mfma_f32_16x16x32_f16 v[114:117], v[146:149], v[204:207], v[114:117]
	v_mfma_f32_16x16x32_f16 v[110:113], v[138:141], v[212:215], v[110:113]
	v_mfma_f32_16x16x32_f16 v[106:109], v[146:149], v[212:215], v[106:109]
	v_mfma_f32_16x16x32_f16 v[102:105], v[138:141], v[230:233], v[102:105]
	v_mfma_f32_16x16x32_f16 v[98:101], v[146:149], v[230:233], v[98:101]
	v_mfma_f32_16x16x32_f16 v[94:97], v[150:153], v[184:187], v[94:97]
	v_mfma_f32_16x16x32_f16 v[90:93], v[176:179], v[184:187], v[90:93]
	v_mfma_f32_16x16x32_f16 v[86:89], v[150:153], v[200:203], v[86:89]
	v_mfma_f32_16x16x32_f16 v[82:85], v[176:179], v[200:203], v[82:85]
	v_mfma_f32_16x16x32_f16 v[78:81], v[150:153], v[208:211], v[78:81]
	v_mfma_f32_16x16x32_f16 v[74:77], v[176:179], v[208:211], v[74:77]
	v_mfma_f32_16x16x32_f16 v[70:73], v[150:153], v[216:219], v[70:73]
	v_mfma_f32_16x16x32_f16 v[66:69], v[176:179], v[216:219], v[66:69]
	v_mfma_f32_16x16x32_f16 v[94:97], v[172:175], v[188:191], v[94:97]
	v_mfma_f32_16x16x32_f16 v[90:93], v[180:183], v[188:191], v[90:93]
	v_mfma_f32_16x16x32_f16 v[86:89], v[172:175], v[204:207], v[86:89]
	v_mfma_f32_16x16x32_f16 v[82:85], v[180:183], v[204:207], v[82:85]
	v_mfma_f32_16x16x32_f16 v[78:81], v[172:175], v[212:215], v[78:81]
	v_mfma_f32_16x16x32_f16 v[74:77], v[180:183], v[212:215], v[74:77]
	v_mfma_f32_16x16x32_f16 v[70:73], v[172:175], v[230:233], v[70:73]
	v_mfma_f32_16x16x32_f16 v[66:69], v[180:183], v[230:233], v[66:69]
	s_barrier
; #define PG8_STAGE(bufoff, gbase) do { _Pragma("unroll") for (int _i = 0; _i < 2; ++_i) \
;         __builtin_amdgcn_global_load_lds((const unsigned*)((const char*)(gbase) + voffA[_i]), (LAS unsigned*)(lds + (bufoff) + ldsw + _i * 8192), 16, 0, 0); } while (0)
; #define PG8_LDA(dst, b, h) do { _Pragma("unroll") for (int m = 0; m < 4; ++m) _Pragma("unroll") for (int k = 0; k < 2; ++k) dst[m][k] = *(const LAS f16x8*)(lds + PG8_SA(b, h) + aoff + m * 2048 + k * 1024); } while (0)
; #define PG8_MMA(ai, bj, At, Bt) do { __builtin_amdgcn_s_setprio(1); _Pragma("unroll") for (int m = 0; m < 4; ++m) _Pragma("unroll") for (int n = 0; n < 2; ++n) _Pragma("unroll") for (int k = 0; k < 2; ++k) \
;         acc[ai][bj][m][n] = __builtin_amdgcn_mfma_f32_16x16x32_f16(Bt[n][k], At[m][k], acc[ai][bj][m][n], 0, 0, 0); __builtin_amdgcn_s_setprio(0); } while (0)
; #define PG8_WAIT_V(n) asm volatile("s_waitcnt vmcnt(" #n ")" ::: "memory")
; #define PG8_WAIT_L(n) asm volatile("s_waitcnt lgkmcnt(" #n ")" ::: "memory")
; #define PG8_BAR __builtin_amdgcn_s_barrier()
; #define PG8_SCHED __builtin_amdgcn_sched_barrier(0)
; template <class Epi, bool SPLITA>
; __device__ __forceinline__ void gemm_phase(LAS unsigned char* lds, const Gemm g, const StaticOrder& S, const Epi& E) {
;     ...
;             PG8_LDA(At, 1, 1); PG8_STAGE(PG8_SB(1, 0), b3); PG8_STAGE(PG8_SB(1, 1), b3 + hstep); PG8_STAGE_A(PG8_SA(1, 0), pm2, kt2 + 1, 0);
;             PG8_WAIT_V(8); PG8_WAIT_L(0); PG8_BAR; PG8_MMA(1, 0, At, B0); PG8_MMA(1, 1, At, B1); PG8_BAR; PG8_SCHED;
;         }
;         if (wr == 0) PG8_BAR;
	s_add_i32 s0, s74, s95
	v_lshl_add_u64 v[164:165], v[164:165], 0, s[88:89]
	s_mov_b32 m0, s0
	ds_read_b128 v[184:187], v171 offset:49152
	ds_read_b128 v[188:191], v171 offset:50176
	ds_read_b128 v[200:203], v171 offset:51200
	ds_read_b128 v[204:207], v171 offset:52224
	ds_read_b128 v[208:211], v171 offset:53248
	ds_read_b128 v[212:215], v171 offset:54272
	ds_read_b128 v[216:219], v171 offset:55296
	ds_read_b128 v[230:233], v171 offset:56320
	global_load_lds_dwordx4 v[164:165], off
	s_add_i32 m0, s0, 0x2000
	s_add_u32 s0, s72, 0x40080
	v_lshl_add_u64 v[164:165], v[192:193], 0, s[88:89]
	s_addc_u32 s1, s73, 0
	s_add_i32 s72, s75, s95
	global_load_lds_dwordx4 v[164:165], off
	v_lshl_add_u64 v[164:165], s[0:1], 0, v[154:155]
	s_mov_b32 m0, s72
	s_nop 0
	global_load_lds_dwordx4 v[164:165], off
	v_lshl_add_u64 v[164:165], s[0:1], 0, v[156:157]
	s_add_i32 m0, s72, 0x2000
	s_nop 0
	global_load_lds_dwordx4 v[164:165], off
	v_lshl_add_u64 v[164:165], v[220:221], 0, s[88:89]
	s_mov_b32 m0, s91
	s_nop 0
	global_load_lds_dwordx4 v[164:165], off
	v_lshl_add_u64 v[164:165], v[234:235], 0, s[88:89]
	s_mov_b32 m0, s92
	s_nop 0
	global_load_lds_dwordx4 v[164:165], off
	s_waitcnt vmcnt(8)
	s_waitcnt lgkmcnt(0)
	s_barrier
	s_waitcnt lgkmcnt(0)
	v_mfma_f32_16x16x32_f16 v[62:65], v[134:137], v[184:187], v[62:65]
	v_mfma_f32_16x16x32_f16 v[58:61], v[142:145], v[184:187], v[58:61]
	v_mfma_f32_16x16x32_f16 v[54:57], v[134:137], v[200:203], v[54:57]
	v_mfma_f32_16x16x32_f16 v[50:53], v[142:145], v[200:203], v[50:53]
	v_mfma_f32_16x16x32_f16 v[46:49], v[134:137], v[208:211], v[46:49]
	v_mfma_f32_16x16x32_f16 v[42:45], v[142:145], v[208:211], v[42:45]
	v_mfma_f32_16x16x32_f16 v[38:41], v[134:137], v[216:219], v[38:41]
	v_mfma_f32_16x16x32_f16 v[34:37], v[142:145], v[216:219], v[34:37]
	v_mfma_f32_16x16x32_f16 v[62:65], v[138:141], v[188:191], v[62:65]
	v_mfma_f32_16x16x32_f16 v[58:61], v[146:149], v[188:191], v[58:61]
	v_mfma_f32_16x16x32_f16 v[54:57], v[138:141], v[204:207], v[54:57]
	v_mfma_f32_16x16x32_f16 v[50:53], v[146:149], v[204:207], v[50:53]
	v_mfma_f32_16x16x32_f16 v[46:49], v[138:141], v[212:215], v[46:49]
	v_mfma_f32_16x16x32_f16 v[42:45], v[146:149], v[212:215], v[42:45]
	v_mfma_f32_16x16x32_f16 v[38:41], v[138:141], v[230:233], v[38:41]
	v_mfma_f32_16x16x32_f16 v[34:37], v[146:149], v[230:233], v[34:37]
	v_mfma_f32_16x16x32_f16 v[30:33], v[150:153], v[184:187], v[30:33]
	v_mfma_f32_16x16x32_f16 v[26:29], v[176:179], v[184:187], v[26:29]
	v_mfma_f32_16x16x32_f16 v[22:25], v[150:153], v[200:203], v[22:25]
	v_mfma_f32_16x16x32_f16 v[18:21], v[176:179], v[200:203], v[18:21]
	v_mfma_f32_16x16x32_f16 v[14:17], v[150:153], v[208:211], v[14:17]
	v_mfma_f32_16x16x32_f16 v[10:13], v[176:179], v[208:211], v[10:13]
	v_mfma_f32_16x16x32_f16 v[6:9], v[150:153], v[216:219], v[6:9]
	v_mfma_f32_16x16x32_f16 v[2:5], v[176:179], v[216:219], v[2:5]
	v_mfma_f32_16x16x32_f16 v[30:33], v[172:175], v[188:191], v[30:33]
	v_mfma_f32_16x16x32_f16 v[26:29], v[180:183], v[188:191], v[26:29]
	v_mfma_f32_16x16x32_f16 v[22:25], v[172:175], v[204:207], v[22:25]
	v_mfma_f32_16x16x32_f16 v[18:21], v[180:183], v[204:207], v[18:21]
	v_mfma_f32_16x16x32_f16 v[14:17], v[172:175], v[212:215], v[14:17]
	v_mfma_f32_16x16x32_f16 v[10:13], v[180:183], v[212:215], v[10:13]
	v_mfma_f32_16x16x32_f16 v[6:9], v[172:175], v[230:233], v[6:9]
	v_mfma_f32_16x16x32_f16 v[2:5], v[180:183], v[230:233], v[2:5]
	s_barrier
	s_add_i32 s71, s71, 2
	s_cmp_gt_u32 s71, 13
	s_mov_b64 s[0:1], s[10:11]
	s_cbranch_scc0 .LBB0_209
	s_and_b64 vcc, exec, s[34:35]
	s_cbranch_vccz .LBB0_212
	s_barrier

; #define PG8_WAIT_V(n) asm volatile("s_waitcnt vmcnt(" #n ")" ::: "memory")
; #define PG8_BAR __builtin_amdgcn_s_barrier()
; template <class Epi, bool SPLITA>
; __device__ __forceinline__ void gemm_phase(LAS unsigned char* lds, const Gemm g, const StaticOrder& S, const Epi& E) {
;     ...
;     PG8_WAIT_V(0);
;     PG8_BAR;
.LBB0_316:
	s_setprio 0
	s_waitcnt vmcnt(0)
	v_readlane_b32 s82, v254, 55
	v_readlane_b32 s86, v254, 57
	v_readlane_b32 s90, v254, 60
	v_readlane_b32 s92, v254, 62
	v_readlane_b32 s6, v255, 2
	v_readlane_b32 s83, v254, 56
	v_readlane_b32 s87, v254, 58
	v_readlane_b32 s85, v254, 59
	v_readlane_b32 s91, v254, 61
	v_readlane_b32 s93, v254, 63
	v_readlane_b32 s99, v255, 4
	v_readlane_b32 s80, v255, 6
	v_readlane_b32 s7, v255, 3
	s_barrier

; #define PG8_STAGE(bufoff, gbase) do { _Pragma("unroll") for (int _i = 0; _i < 2; ++_i) \
;         __builtin_amdgcn_global_load_lds((const unsigned*)((const char*)(gbase) + voffA[_i]), (LAS unsigned*)(lds + (bufoff) + ldsw + _i * 8192), 16, 0, 0); } while (0)
; #define PG8_WAIT_V(n) asm volatile("s_waitcnt vmcnt(" #n ")" ::: "memory")
; #define PG8_BAR __builtin_amdgcn_s_barrier()
; template <class Epi, bool SPLITA>
; __device__ __forceinline__ void gemm_phase(LAS unsigned char* lds, const Gemm g, const StaticOrder& S, const Epi& E) {
;     ...
;     const char* cB = (const char*)g.Bt + (size_t)cur.pn * tstep;
;     PG8_STAGE(PG8_SB(0, 0), cB); PG8_STAGE(PG8_SB(0, 1), cB + hstep); PG8_STAGE_A(PG8_SA(0, 0), cur.pm, 0, 0); PG8_STAGE_A(PG8_SA(0, 1), cur.pm, 0, 1);
;     if (wr == 1) PG8_BAR;
;     PG8_WAIT_V(2); PG8_BAR;
;     PG8_STAGE(PG8_SB(1, 0), cB + kstep); PG8_STAGE_A(PG8_SA(1, 0), cur.pm, 1, 0); PG8_STAGE(PG8_SB(1, 1), cB + hstep + kstep);
;     PG8_WAIT_V(6); PG8_BAR;
.LBB0_477:
	v_lshl_add_u64 v[8:9], s[76:77], 0, v[194:195]
	v_mov_b32_e32 v203, v195
	v_readlane_b32 s6, v254, 35
	s_add_i32 s53, s12, 0x18000
	v_lshl_add_u64 v[10:11], s[76:77], 0, v[202:203]
	v_mov_b32_e32 v205, v195
	v_readlane_b32 s7, v254, 36
	v_mov_b32_e32 v201, v195
	s_and_b32 s1, s1, 3
	v_lshl_add_u64 v[8:9], v[8:9], 0, s[88:89]
	s_mov_b32 m0, s53
	s_add_i32 s64, s12, 0x1a000
	v_lshl_add_u64 v[12:13], s[6:7], 0, v[204:205]
	v_lshl_add_u64 v[14:15], s[6:7], 0, v[200:201]
	s_lshl_b32 s52, s4, 6
	s_lshl_b32 s6, s4, 13
	s_lshl_b32 s7, s1, 12
	s_waitcnt vmcnt(2)
	s_barrier
	global_load_lds_dwordx4 v[8:9], off
	v_lshl_add_u64 v[8:9], v[10:11], 0, s[88:89]
	s_mov_b32 m0, s64
	s_add_i32 s65, s12, 0x8000
	s_add_i32 s85, s12, 0xa000
	global_load_lds_dwordx4 v[8:9], off
	v_lshl_add_u64 v[8:9], v[12:13], 0, s[88:89]
	s_mov_b32 m0, s65
	s_add_u32 s4, s76, 0x40080
	global_load_lds_dwordx4 v[8:9], off
	v_lshl_add_u64 v[8:9], v[14:15], 0, s[88:89]
	s_mov_b32 m0, s85
	s_addc_u32 s5, s77, 0
	s_add_i32 s86, s12, 0x1c000
	global_load_lds_dwordx4 v[8:9], off
	v_lshl_add_u64 v[8:9], s[4:5], 0, v[194:195]
	s_mov_b32 m0, s86
	s_add_i32 s87, s12, 0x1e000
	global_load_lds_dwordx4 v[8:9], off
	v_lshl_add_u64 v[8:9], s[4:5], 0, v[202:203]
	s_mov_b32 m0, s87
	v_lshlrev_b32_e32 v4, 13, v4
	global_load_lds_dwordx4 v[8:9], off
	v_and_b32_e32 v4, 0xffff0000, v4
	v_lshl_add_u32 v206, v3, 4, v4
	v_lshlrev_b32_e32 v3, 13, v6
	v_and_b32_e32 v3, 0xffff0000, v3
	v_bfe_u32 v231, v2, 4, 2
	s_cmpk_lt_u32 s0, 0x100
	v_readlane_b32 s4, v254, 51
	v_lshl_add_u32 v208, v5, 4, v3
	v_and_b32_e32 v230, 15, v2
	v_lshlrev_b32_e32 v3, 4, v231
	v_lshlrev_b32_e32 v2, 2, v2
	s_cselect_b64 s[68:69], -1, 0
	v_readlane_b32 s5, v254, 52
	s_lshl_b32 s4, s1, 2
	v_lshl_or_b32 v3, v230, 6, v3
	v_and_b32_e32 v2, 32, v2
	s_waitcnt vmcnt(6)
	v_writelane_b32 v254, s4, 51
	v_bitop3_b32 v4, v3, s6, v2 bitop3:0xde
	v_bitop3_b32 v2, v3, s7, v2 bitop3:0xde
	v_writelane_b32 v254, s5, 52
	s_lshl_b32 s90, s1, 6
	v_mov_b32_e32 v207, v195
	v_mov_b32_e32 v209, v195
	s_waitcnt lgkmcnt(0)
	s_ashr_i32 s91, s46, 31
	s_mov_b32 s92, 0
	v_add_u32_e32 v232, 0, v2
	v_add_u32_e32 v233, 0, v4
	v_readlane_b32 s94, v254, 30
	v_readlane_b32 s0, v254, 33
	s_barrier
	v_readlane_b32 s1, v254, 34
	v_and_b32_e32 v252, 15, v0
	v_bfe_u32 v253, v0, 4, 2
	v_lshlrev_b32_e32 v253, 2, v253
	v_sub_u32_e32 v252, v252, v253
	v_mov_b32_e32 v253, 0x3c00
	v_cmp_eq_u32_e32 vcc, 0, v252
	s_nop 1
	v_cndmask_b32_e32 v198, 0, v253, vcc
	v_cmp_eq_u32_e32 vcc, 2, v252
	s_nop 1
	v_cndmask_b32_e32 v199, 0, v253, vcc
	v_mov_b32_e32 v253, 0x3c000000
	v_cmp_eq_u32_e32 vcc, 1, v252
	s_nop 1
	v_cndmask_b32_e32 v198, v198, v253, vcc
	v_cmp_eq_u32_e32 vcc, 3, v252
	s_nop 1
	v_cndmask_b32_e32 v199, v199, v253, vcc
	v_lshrrev_b32_e32 v252, 8, v0
	v_lshlrev_b32_e32 v253, 17, v252
	v_and_b32_e32 v252, 15, v0
	v_lshl_or_b32 v253, v252, 11, v253
	v_bfe_u32 v252, v0, 6, 2
	v_lshl_or_b32 v253, v252, 7, v253
	v_bfe_u32 v252, v0, 4, 2
	v_lshl_or_b32 v253, v252, 4, v253
	v_readfirstlane_b32 s100, v0
	s_nop 3
	s_cmp_ge_u32 s100, 0x100
	s_cbranch_scc0 .Lprio_skip0
	s_setprio 1
.Lprio_skip0:
	s_branch .LBB0_480
.LBB0_478:
	s_mov_b64 s[0:1], 0

; #define PG8_STAGE(bufoff, gbase) do { _Pragma("unroll") for (int _i = 0; _i < 2; ++_i) \
;         __builtin_amdgcn_global_load_lds((const unsigned*)((const char*)(gbase) + voffA[_i]), (LAS unsigned*)(lds + (bufoff) + ldsw + _i * 8192), 16, 0, 0); } while (0)
; #define PG8_LDA(dst, b, h) do { _Pragma("unroll") for (int m = 0; m < 4; ++m) _Pragma("unroll") for (int k = 0; k < 2; ++k) dst[m][k] = *(const LAS f16x8*)(lds + PG8_SA(b, h) + aoff + m * 2048 + k * 1024); } while (0)
; #define PG8_MMA(ai, bj, At, Bt) do { __builtin_amdgcn_s_setprio(1); _Pragma("unroll") for (int m = 0; m < 4; ++m) _Pragma("unroll") for (int n = 0; n < 2; ++n) _Pragma("unroll") for (int k = 0; k < 2; ++k) \
;         acc[ai][bj][m][n] = __builtin_amdgcn_mfma_f32_16x16x32_f16(Bt[n][k], At[m][k], acc[ai][bj][m][n], 0, 0, 0); __builtin_amdgcn_s_setprio(0); } while (0)
; #define PG8_WAIT_V(n) asm volatile("s_waitcnt vmcnt(" #n ")" ::: "memory")
; #define PG8_WAIT_L(n) asm volatile("s_waitcnt lgkmcnt(" #n ")" ::: "memory")
; #define PG8_BAR __builtin_amdgcn_s_barrier()
; #define PG8_SCHED __builtin_amdgcn_sched_barrier(0)
; template <class Epi, bool SPLITA>
; __device__ __forceinline__ void gemm_phase(LAS unsigned char* lds, const Gemm g, const StaticOrder& S, const Epi& E) {
;     ...
;             PG8_WAIT_V(8); PG8_WAIT_L(0); PG8_BAR; PG8_MMA(0, 0, At, B0); PG8_MMA(0, 1, At, B1); PG8_BAR; PG8_SCHED;
;             PG8_LDA(At, 1, 1); PG8_STAGE(PG8_SB(1, 0), b3); PG8_STAGE(PG8_SB(1, 1), b3 + hstep); PG8_STAGE_A(PG8_SA(1, 0), pm2, kt2 + 1, 0);
;             PG8_WAIT_V(8); PG8_WAIT_L(0); PG8_BAR; PG8_MMA(1, 0, At, B0); PG8_MMA(1, 1, At, B1); PG8_BAR; PG8_SCHED;
.LBB0_483:
	s_mov_b32 m0, s65
	v_lshl_add_u64 v[196:197], s[78:79], 0, v[212:213]
	global_load_lds_dwordx4 v[196:197], off
	v_lshl_add_u64 v[196:197], s[78:79], 0, v[210:211]
	s_mov_b32 m0, s85
	s_nop 0
	global_load_lds_dwordx4 v[196:197], off
	s_waitcnt vmcnt(8)
	s_waitcnt lgkmcnt(0)
	s_barrier
	s_waitcnt lgkmcnt(0)
	v_mfma_f32_16x16x32_f16 v[62:65], v[146:149], v[186:189], v[62:65]
	v_mfma_f32_16x16x32_f16 v[58:61], v[154:157], v[186:189], v[58:61]
	v_mfma_f32_16x16x32_f16 v[46:49], v[146:149], v[178:181], v[46:49]
	v_mfma_f32_16x16x32_f16 v[42:45], v[154:157], v[178:181], v[42:45]
	v_mfma_f32_16x16x32_f16 v[30:33], v[146:149], v[170:173], v[30:33]
	v_mfma_f32_16x16x32_f16 v[26:29], v[154:157], v[170:173], v[26:29]
	v_mfma_f32_16x16x32_f16 v[14:17], v[146:149], v[162:165], v[14:17]
	v_mfma_f32_16x16x32_f16 v[10:13], v[154:157], v[162:165], v[10:13]
	v_mfma_f32_16x16x32_f16 v[62:65], v[150:153], v[190:193], v[62:65]
	v_mfma_f32_16x16x32_f16 v[58:61], v[158:161], v[190:193], v[58:61]
	v_mfma_f32_16x16x32_f16 v[46:49], v[150:153], v[182:185], v[46:49]
	v_mfma_f32_16x16x32_f16 v[42:45], v[158:161], v[182:185], v[42:45]
	v_mfma_f32_16x16x32_f16 v[30:33], v[150:153], v[174:177], v[30:33]
	v_mfma_f32_16x16x32_f16 v[26:29], v[158:161], v[174:177], v[26:29]
	v_mfma_f32_16x16x32_f16 v[14:17], v[150:153], v[166:169], v[14:17]
	v_mfma_f32_16x16x32_f16 v[10:13], v[158:161], v[166:169], v[10:13]
	v_mfma_f32_16x16x32_f16 v[54:57], v[130:133], v[186:189], v[54:57]
	v_mfma_f32_16x16x32_f16 v[50:53], v[138:141], v[186:189], v[50:53]
	v_mfma_f32_16x16x32_f16 v[38:41], v[130:133], v[178:181], v[38:41]
	v_mfma_f32_16x16x32_f16 v[34:37], v[138:141], v[178:181], v[34:37]
	v_mfma_f32_16x16x32_f16 v[22:25], v[130:133], v[170:173], v[22:25]
	v_mfma_f32_16x16x32_f16 v[18:21], v[138:141], v[170:173], v[18:21]
	v_mfma_f32_16x16x32_f16 v[6:9], v[130:133], v[162:165], v[6:9]
	v_mfma_f32_16x16x32_f16 v[2:5], v[138:141], v[162:165], v[2:5]
	v_mfma_f32_16x16x32_f16 v[54:57], v[134:137], v[190:193], v[54:57]
	v_mfma_f32_16x16x32_f16 v[50:53], v[142:145], v[190:193], v[50:53]
	v_mfma_f32_16x16x32_f16 v[38:41], v[134:137], v[182:185], v[38:41]
	v_mfma_f32_16x16x32_f16 v[34:37], v[142:145], v[182:185], v[34:37]
	v_mfma_f32_16x16x32_f16 v[22:25], v[134:137], v[174:177], v[22:25]
	v_mfma_f32_16x16x32_f16 v[18:21], v[142:145], v[174:177], v[18:21]
	v_mfma_f32_16x16x32_f16 v[6:9], v[134:137], v[166:169], v[6:9]
	v_mfma_f32_16x16x32_f16 v[2:5], v[142:145], v[166:169], v[2:5]
	s_barrier
	s_add_u32 s72, s72, 0x100
	s_addc_u32 s73, s73, 0
	s_add_i32 s35, s35, 2
	s_add_u32 s11, s11, 0x100
	s_addc_u32 s34, s34, 0
	s_cmp_gt_u32 s6, 13
	s_mov_b32 s6, s7
	s_cbranch_scc1 .LBB0_498

; #define PG8_STAGE(bufoff, gbase) do { _Pragma("unroll") for (int _i = 0; _i < 2; ++_i) \
;         __builtin_amdgcn_global_load_lds((const unsigned*)((const char*)(gbase) + voffA[_i]), (LAS unsigned*)(lds + (bufoff) + ldsw + _i * 8192), 16, 0, 0); } while (0)
; #define PG8_LDA(dst, b, h) do { _Pragma("unroll") for (int m = 0; m < 4; ++m) _Pragma("unroll") for (int k = 0; k < 2; ++k) dst[m][k] = *(const LAS f16x8*)(lds + PG8_SA(b, h) + aoff + m * 2048 + k * 1024); } while (0)
; #define PG8_LDB(dst, b, h) do { _Pragma("unroll") for (int n = 0; n < 2; ++n) _Pragma("unroll") for (int k = 0; k < 2; ++k) dst[n][k] = *(const LAS f16x8*)(lds + PG8_SB(b, h) + boff + n * 2048 + k * 1024); } while (0)
; #define PG8_MMA(ai, bj, At, Bt) do { __builtin_amdgcn_s_setprio(1); _Pragma("unroll") for (int m = 0; m < 4; ++m) _Pragma("unroll") for (int n = 0; n < 2; ++n) _Pragma("unroll") for (int k = 0; k < 2; ++k) \
;         acc[ai][bj][m][n] = __builtin_amdgcn_mfma_f32_16x16x32_f16(Bt[n][k], At[m][k], acc[ai][bj][m][n], 0, 0, 0); __builtin_amdgcn_s_setprio(0); } while (0)
; #define PG8_WAIT_V(n) asm volatile("s_waitcnt vmcnt(" #n ")" ::: "memory")
; #define PG8_WAIT_L(n) asm volatile("s_waitcnt lgkmcnt(" #n ")" ::: "memory")
; #define PG8_BAR __builtin_amdgcn_s_barrier()
; #define PG8_SCHED __builtin_amdgcn_sched_barrier(0)
; template <class Epi, bool SPLITA>
; __device__ __forceinline__ void gemm_phase(LAS unsigned char* lds, const Gemm g, const StaticOrder& S, const Epi& E) {
;     ...
;             PG8_LDB(B0, 0, 0); PG8_LDB(B1, 0, 1); PG8_SCHED; PG8_LDA(At, 0, 0); PG8_STAGE_A(PG8_SA(1, 1), cur.pm, t + 1, 1);
;             PG8_WAIT_V(8); PG8_WAIT_L(0); PG8_BAR; PG8_MMA(0, 0, At, B0); PG8_MMA(0, 1, At, B1); PG8_BAR; PG8_SCHED;
;             PG8_LDA(At, 0, 1); PG8_STAGE(PG8_SB(0, 0), b2); PG8_STAGE(PG8_SB(0, 1), b2 + hstep); PG8_STAGE_A(PG8_SA(0, 0), pm2, kt2, 0);
;             PG8_WAIT_V(8); PG8_WAIT_L(0); PG8_BAR; PG8_MMA(1, 0, At, B0); PG8_MMA(1, 1, At, B1); PG8_BAR; PG8_SCHED;
.LBB0_486:
	s_add_i32 s7, s6, 2
	s_cmp_eq_u32 s35, 7
	s_cselect_b32 s79, s71, s34
	s_cselect_b32 s78, s98, s11
	s_cselect_b32 s66, 0, s7
	s_cselect_b32 s76, s95, s0
	v_lshl_add_u64 v[196:197], s[80:81], 0, v[212:213]
	s_add_i32 m0, s12, 0xc000
	s_nop 0
	global_load_lds_dwordx4 v[196:197], off
	v_lshl_add_u64 v[196:197], s[80:81], 0, v[210:211]
	s_add_i32 m0, s12, 0xe000
	s_nop 0
	global_load_lds_dwordx4 v[196:197], off
	s_waitcnt vmcnt(10)
	s_waitcnt lgkmcnt(0)
	s_barrier
	s_waitcnt lgkmcnt(0)
	v_mfma_f32_16x16x32_f16 v[126:129], v[146:149], v[186:189], v[126:129]
	v_mfma_f32_16x16x32_f16 v[122:125], v[154:157], v[186:189], v[122:125]
	v_mfma_f32_16x16x32_f16 v[110:113], v[146:149], v[178:181], v[110:113]
	v_mfma_f32_16x16x32_f16 v[106:109], v[154:157], v[178:181], v[106:109]
	v_mfma_f32_16x16x32_f16 v[94:97], v[146:149], v[170:173], v[94:97]
	v_mfma_f32_16x16x32_f16 v[90:93], v[154:157], v[170:173], v[90:93]
	v_mfma_f32_16x16x32_f16 v[78:81], v[146:149], v[162:165], v[78:81]
	v_mfma_f32_16x16x32_f16 v[74:77], v[154:157], v[162:165], v[74:77]
	v_mfma_f32_16x16x32_f16 v[126:129], v[150:153], v[190:193], v[126:129]
	v_mfma_f32_16x16x32_f16 v[122:125], v[158:161], v[190:193], v[122:125]
	v_mfma_f32_16x16x32_f16 v[110:113], v[150:153], v[182:185], v[110:113]
	v_mfma_f32_16x16x32_f16 v[106:109], v[158:161], v[182:185], v[106:109]
	v_mfma_f32_16x16x32_f16 v[94:97], v[150:153], v[174:177], v[94:97]
	v_mfma_f32_16x16x32_f16 v[90:93], v[158:161], v[174:177], v[90:93]
	v_mfma_f32_16x16x32_f16 v[78:81], v[150:153], v[166:169], v[78:81]
	v_mfma_f32_16x16x32_f16 v[74:77], v[158:161], v[166:169], v[74:77]
	v_mfma_f32_16x16x32_f16 v[118:121], v[130:133], v[186:189], v[118:121]
	v_mfma_f32_16x16x32_f16 v[114:117], v[138:141], v[186:189], v[114:117]
	v_mfma_f32_16x16x32_f16 v[102:105], v[130:133], v[178:181], v[102:105]
	v_mfma_f32_16x16x32_f16 v[98:101], v[138:141], v[178:181], v[98:101]
	v_mfma_f32_16x16x32_f16 v[86:89], v[130:133], v[170:173], v[86:89]
	v_mfma_f32_16x16x32_f16 v[82:85], v[138:141], v[170:173], v[82:85]
	v_mfma_f32_16x16x32_f16 v[70:73], v[130:133], v[162:165], v[70:73]
	v_mfma_f32_16x16x32_f16 v[66:69], v[138:141], v[162:165], v[66:69]
	v_mfma_f32_16x16x32_f16 v[118:121], v[134:137], v[190:193], v[118:121]
	v_mfma_f32_16x16x32_f16 v[114:117], v[142:145], v[190:193], v[114:117]
	v_mfma_f32_16x16x32_f16 v[102:105], v[134:137], v[182:185], v[102:105]
	v_mfma_f32_16x16x32_f16 v[98:101], v[142:145], v[182:185], v[98:101]
	v_mfma_f32_16x16x32_f16 v[86:89], v[134:137], v[174:177], v[86:89]
	v_mfma_f32_16x16x32_f16 v[82:85], v[142:145], v[174:177], v[82:85]
	v_mfma_f32_16x16x32_f16 v[70:73], v[134:137], v[166:169], v[70:73]
	v_mfma_f32_16x16x32_f16 v[66:69], v[142:145], v[166:169], v[66:69]
	s_barrier
	v_lshl_add_u64 v[210:211], s[78:79], 0, v[194:195]
	s_mov_b32 m0, s13
	s_add_u32 s80, s78, 0x40000
	ds_read_b128 v[186:189], v233 offset:16384
	ds_read_b128 v[190:193], v233 offset:17408
	ds_read_b128 v[178:181], v233 offset:18432
	ds_read_b128 v[182:185], v233 offset:19456
	ds_read_b128 v[170:173], v233 offset:20480
	ds_read_b128 v[174:177], v233 offset:21504
	ds_read_b128 v[162:165], v233 offset:22528
	ds_read_b128 v[166:169], v233 offset:23552
	global_load_lds_dwordx4 v[210:211], off
	v_lshl_add_u64 v[212:213], s[78:79], 0, v[202:203]
	s_mov_b32 m0, s14
	s_addc_u32 s81, s79, 0
	global_load_lds_dwordx4 v[212:213], off
	v_lshl_add_u64 v[196:197], s[80:81], 0, v[194:195]
	s_mov_b32 m0, s15
	s_cmp_lt_u32 s66, 8
	global_load_lds_dwordx4 v[196:197], off
	v_lshl_add_u64 v[196:197], s[80:81], 0, v[202:203]
	s_mov_b32 m0, s31
	s_cselect_b64 s[80:81], -1, 0
	global_load_lds_dwordx4 v[196:197], off
	s_mov_b64 s[96:97], -1
	s_and_b64 vcc, exec, s[80:81]
	s_cbranch_vccz .LBB0_488
	s_ashr_i32 s77, s76, 31
	s_lshl_b64 s[82:83], s[76:77], 18
	s_add_u32 s67, s62, s82
	s_addc_u32 s77, s63, s83
	s_lshl_b32 s82, s66, 7
	s_add_u32 s82, s67, s82
	s_addc_u32 s83, s77, 0
	s_mov_b64 s[96:97], 0

; #define PG8_LDA(dst, b, h) do { _Pragma("unroll") for (int m = 0; m < 4; ++m) _Pragma("unroll") for (int k = 0; k < 2; ++k) dst[m][k] = *(const LAS f16x8*)(lds + PG8_SA(b, h) + aoff + m * 2048 + k * 1024); } while (0)
; #define PG8_LDB(dst, b, h) do { _Pragma("unroll") for (int n = 0; n < 2; ++n) _Pragma("unroll") for (int k = 0; k < 2; ++k) dst[n][k] = *(const LAS f16x8*)(lds + PG8_SB(b, h) + boff + n * 2048 + k * 1024); } while (0)
; #define PG8_MMA(ai, bj, At, Bt) do { __builtin_amdgcn_s_setprio(1); _Pragma("unroll") for (int m = 0; m < 4; ++m) _Pragma("unroll") for (int n = 0; n < 2; ++n) _Pragma("unroll") for (int k = 0; k < 2; ++k) \
;         acc[ai][bj][m][n] = __builtin_amdgcn_mfma_f32_16x16x32_f16(Bt[n][k], At[m][k], acc[ai][bj][m][n], 0, 0, 0); __builtin_amdgcn_s_setprio(0); } while (0)
; #define PG8_WAIT_V(n) asm volatile("s_waitcnt vmcnt(" #n ")" ::: "memory")
; #define PG8_WAIT_L(n) asm volatile("s_waitcnt lgkmcnt(" #n ")" ::: "memory")
; #define PG8_BAR __builtin_amdgcn_s_barrier()
; #define PG8_SCHED __builtin_amdgcn_sched_barrier(0)
; template <class Epi, bool SPLITA>
; __device__ __forceinline__ void gemm_phase(LAS unsigned char* lds, const Gemm g, const StaticOrder& S, const Epi& E) {
;     ...
;             PG8_WAIT_V(8); PG8_WAIT_L(0); PG8_BAR; PG8_MMA(1, 0, At, B0); PG8_MMA(1, 1, At, B1); PG8_BAR; PG8_SCHED;
;             PG8_LDB(B0, 1, 0); PG8_LDB(B1, 1, 1); PG8_SCHED; PG8_LDA(At, 1, 0); PG8_STAGE_A(PG8_SA(0, 1), pm2, kt2, 1);
;             PG8_WAIT_V(8); PG8_WAIT_L(0); PG8_BAR; PG8_MMA(0, 0, At, B0); PG8_MMA(0, 1, At, B1); PG8_BAR; PG8_SCHED;
.LBB0_490:
	s_mov_b32 m0, s12
	v_lshl_add_u64 v[196:197], s[82:83], 0, v[216:217]
	global_load_lds_dwordx4 v[196:197], off
	v_lshl_add_u64 v[196:197], s[82:83], 0, v[214:215]
	s_mov_b32 m0, s33
	s_nop 0
	global_load_lds_dwordx4 v[196:197], off
	s_waitcnt vmcnt(10)
	s_waitcnt lgkmcnt(0)
	s_barrier
	s_waitcnt lgkmcnt(0)
	v_mfma_f32_16x16x32_f16 v[62:65], v[146:149], v[186:189], v[62:65]
	v_mfma_f32_16x16x32_f16 v[58:61], v[154:157], v[186:189], v[58:61]
	v_mfma_f32_16x16x32_f16 v[46:49], v[146:149], v[178:181], v[46:49]
	v_mfma_f32_16x16x32_f16 v[42:45], v[154:157], v[178:181], v[42:45]
	v_mfma_f32_16x16x32_f16 v[30:33], v[146:149], v[170:173], v[30:33]
	v_mfma_f32_16x16x32_f16 v[26:29], v[154:157], v[170:173], v[26:29]
	v_mfma_f32_16x16x32_f16 v[14:17], v[146:149], v[162:165], v[14:17]
	v_mfma_f32_16x16x32_f16 v[10:13], v[154:157], v[162:165], v[10:13]
	v_mfma_f32_16x16x32_f16 v[62:65], v[150:153], v[190:193], v[62:65]
	v_mfma_f32_16x16x32_f16 v[58:61], v[158:161], v[190:193], v[58:61]
	v_mfma_f32_16x16x32_f16 v[46:49], v[150:153], v[182:185], v[46:49]
	v_mfma_f32_16x16x32_f16 v[42:45], v[158:161], v[182:185], v[42:45]
	v_mfma_f32_16x16x32_f16 v[30:33], v[150:153], v[174:177], v[30:33]
	v_mfma_f32_16x16x32_f16 v[26:29], v[158:161], v[174:177], v[26:29]
	v_mfma_f32_16x16x32_f16 v[14:17], v[150:153], v[166:169], v[14:17]
	v_mfma_f32_16x16x32_f16 v[10:13], v[158:161], v[166:169], v[10:13]
	v_mfma_f32_16x16x32_f16 v[54:57], v[130:133], v[186:189], v[54:57]
	v_mfma_f32_16x16x32_f16 v[50:53], v[138:141], v[186:189], v[50:53]
	v_mfma_f32_16x16x32_f16 v[38:41], v[130:133], v[178:181], v[38:41]
	v_mfma_f32_16x16x32_f16 v[34:37], v[138:141], v[178:181], v[34:37]
	v_mfma_f32_16x16x32_f16 v[22:25], v[130:133], v[170:173], v[22:25]
	v_mfma_f32_16x16x32_f16 v[18:21], v[138:141], v[170:173], v[18:21]
	v_mfma_f32_16x16x32_f16 v[6:9], v[130:133], v[162:165], v[6:9]
	v_mfma_f32_16x16x32_f16 v[2:5], v[138:141], v[162:165], v[2:5]
	v_mfma_f32_16x16x32_f16 v[54:57], v[134:137], v[190:193], v[54:57]
	v_mfma_f32_16x16x32_f16 v[50:53], v[142:145], v[190:193], v[50:53]
	v_mfma_f32_16x16x32_f16 v[38:41], v[134:137], v[182:185], v[38:41]
	v_mfma_f32_16x16x32_f16 v[34:37], v[142:145], v[182:185], v[34:37]
	v_mfma_f32_16x16x32_f16 v[22:25], v[134:137], v[174:177], v[22:25]
	v_mfma_f32_16x16x32_f16 v[18:21], v[142:145], v[174:177], v[18:21]
	v_mfma_f32_16x16x32_f16 v[6:9], v[134:137], v[166:169], v[6:9]
	v_mfma_f32_16x16x32_f16 v[2:5], v[142:145], v[166:169], v[2:5]
	s_barrier
	v_add_u32_e32 v130, 0x18000, v232
	v_add_u32_e32 v142, 0x1c000, v232
	ds_read_b128 v[146:149], v130
	ds_read_b128 v[150:153], v130 offset:1024
	ds_read_b128 v[154:157], v130 offset:2048
	ds_read_b128 v[158:161], v130 offset:3072
	ds_read_b128 v[130:133], v142
	ds_read_b128 v[134:137], v142 offset:1024
	ds_read_b128 v[138:141], v142 offset:2048
	ds_read_b128 v[142:145], v142 offset:3072
	ds_read_b128 v[186:189], v233 offset:32768
	ds_read_b128 v[190:193], v233 offset:33792
	ds_read_b128 v[178:181], v233 offset:34816
	ds_read_b128 v[182:185], v233 offset:35840
	ds_read_b128 v[170:173], v233 offset:36864
	ds_read_b128 v[174:177], v233 offset:37888
	ds_read_b128 v[162:165], v233 offset:38912
	ds_read_b128 v[166:169], v233 offset:39936
	s_mov_b64 s[96:97], -1
	s_and_b64 vcc, exec, s[80:81]
	s_cbranch_vccz .LBB0_492
	s_ashr_i32 s77, s76, 31
	s_lshl_b64 s[82:83], s[76:77], 18
	s_add_u32 s67, s62, s82
	s_addc_u32 s77, s63, s83
	s_lshl_b32 s82, s66, 7
	s_add_u32 s67, s67, s82
	s_addc_u32 s77, s77, 0
	s_add_u32 s82, s67, 0x20000
	s_addc_u32 s83, s77, 0
	s_mov_b64 s[96:97], 0

; #define PG8_STAGE(bufoff, gbase) do { _Pragma("unroll") for (int _i = 0; _i < 2; ++_i) \
;         __builtin_amdgcn_global_load_lds((const unsigned*)((const char*)(gbase) + voffA[_i]), (LAS unsigned*)(lds + (bufoff) + ldsw + _i * 8192), 16, 0, 0); } while (0)
; #define PG8_LDA(dst, b, h) do { _Pragma("unroll") for (int m = 0; m < 4; ++m) _Pragma("unroll") for (int k = 0; k < 2; ++k) dst[m][k] = *(const LAS f16x8*)(lds + PG8_SA(b, h) + aoff + m * 2048 + k * 1024); } while (0)
; #define PG8_MMA(ai, bj, At, Bt) do { __builtin_amdgcn_s_setprio(1); _Pragma("unroll") for (int m = 0; m < 4; ++m) _Pragma("unroll") for (int n = 0; n < 2; ++n) _Pragma("unroll") for (int k = 0; k < 2; ++k) \
;         acc[ai][bj][m][n] = __builtin_amdgcn_mfma_f32_16x16x32_f16(Bt[n][k], At[m][k], acc[ai][bj][m][n], 0, 0, 0); __builtin_amdgcn_s_setprio(0); } while (0)
; #define PG8_WAIT_V(n) asm volatile("s_waitcnt vmcnt(" #n ")" ::: "memory")
; #define PG8_WAIT_L(n) asm volatile("s_waitcnt lgkmcnt(" #n ")" ::: "memory")
; #define PG8_BAR __builtin_amdgcn_s_barrier()
; #define PG8_SCHED __builtin_amdgcn_sched_barrier(0)
; template <class Epi, bool SPLITA>
; __device__ __forceinline__ void gemm_phase(LAS unsigned char* lds, const Gemm g, const StaticOrder& S, const Epi& E) {
;     ...
;             PG8_WAIT_V(8); PG8_WAIT_L(0); PG8_BAR; PG8_MMA(0, 0, At, B0); PG8_MMA(0, 1, At, B1); PG8_BAR; PG8_SCHED;
;             PG8_LDA(At, 1, 1); PG8_STAGE(PG8_SB(1, 0), b3); PG8_STAGE(PG8_SB(1, 1), b3 + hstep); PG8_STAGE_A(PG8_SA(1, 0), pm2, kt2 + 1, 0);
;             PG8_WAIT_V(8); PG8_WAIT_L(0); PG8_BAR; PG8_MMA(1, 0, At, B0); PG8_MMA(1, 1, At, B1); PG8_BAR; PG8_SCHED;
.LBB0_494:
	s_mov_b32 m0, s36
	v_lshl_add_u64 v[196:197], s[82:83], 0, v[216:217]
	global_load_lds_dwordx4 v[196:197], off
	v_lshl_add_u64 v[196:197], s[82:83], 0, v[214:215]
	s_mov_b32 m0, s37
	s_nop 0
	global_load_lds_dwordx4 v[196:197], off
	s_waitcnt vmcnt(8)
	s_waitcnt lgkmcnt(0)
	s_barrier
	s_waitcnt lgkmcnt(0)
	v_mfma_f32_16x16x32_f16 v[126:129], v[146:149], v[186:189], v[126:129]
	v_mfma_f32_16x16x32_f16 v[122:125], v[154:157], v[186:189], v[122:125]
	v_mfma_f32_16x16x32_f16 v[110:113], v[146:149], v[178:181], v[110:113]
	v_mfma_f32_16x16x32_f16 v[106:109], v[154:157], v[178:181], v[106:109]
	v_mfma_f32_16x16x32_f16 v[94:97], v[146:149], v[170:173], v[94:97]
	v_mfma_f32_16x16x32_f16 v[90:93], v[154:157], v[170:173], v[90:93]
	v_mfma_f32_16x16x32_f16 v[78:81], v[146:149], v[162:165], v[78:81]
	v_mfma_f32_16x16x32_f16 v[74:77], v[154:157], v[162:165], v[74:77]
	v_mfma_f32_16x16x32_f16 v[126:129], v[150:153], v[190:193], v[126:129]
	v_mfma_f32_16x16x32_f16 v[122:125], v[158:161], v[190:193], v[122:125]
	v_mfma_f32_16x16x32_f16 v[110:113], v[150:153], v[182:185], v[110:113]
	v_mfma_f32_16x16x32_f16 v[106:109], v[158:161], v[182:185], v[106:109]
	v_mfma_f32_16x16x32_f16 v[94:97], v[150:153], v[174:177], v[94:97]
	v_mfma_f32_16x16x32_f16 v[90:93], v[158:161], v[174:177], v[90:93]
	v_mfma_f32_16x16x32_f16 v[78:81], v[150:153], v[166:169], v[78:81]
	v_mfma_f32_16x16x32_f16 v[74:77], v[158:161], v[166:169], v[74:77]
	v_mfma_f32_16x16x32_f16 v[118:121], v[130:133], v[186:189], v[118:121]
	v_mfma_f32_16x16x32_f16 v[114:117], v[138:141], v[186:189], v[114:117]
	v_mfma_f32_16x16x32_f16 v[102:105], v[130:133], v[178:181], v[102:105]
	v_mfma_f32_16x16x32_f16 v[98:101], v[138:141], v[178:181], v[98:101]
	v_mfma_f32_16x16x32_f16 v[86:89], v[130:133], v[170:173], v[86:89]
	v_mfma_f32_16x16x32_f16 v[82:85], v[138:141], v[170:173], v[82:85]
	v_mfma_f32_16x16x32_f16 v[70:73], v[130:133], v[162:165], v[70:73]
	v_mfma_f32_16x16x32_f16 v[66:69], v[138:141], v[162:165], v[66:69]
	v_mfma_f32_16x16x32_f16 v[118:121], v[134:137], v[190:193], v[118:121]
	v_mfma_f32_16x16x32_f16 v[114:117], v[142:145], v[190:193], v[114:117]
	v_mfma_f32_16x16x32_f16 v[102:105], v[134:137], v[182:185], v[102:105]
	v_mfma_f32_16x16x32_f16 v[98:101], v[142:145], v[182:185], v[98:101]
	v_mfma_f32_16x16x32_f16 v[86:89], v[134:137], v[174:177], v[86:89]
	v_mfma_f32_16x16x32_f16 v[82:85], v[142:145], v[174:177], v[82:85]
	v_mfma_f32_16x16x32_f16 v[70:73], v[134:137], v[166:169], v[70:73]
	v_mfma_f32_16x16x32_f16 v[66:69], v[142:145], v[166:169], v[66:69]
	s_cmp_lt_u32 s6, 8
	s_cbranch_scc0 .Lres_hi
	s_cmp_lt_u32 s6, 4
	s_cbranch_scc0 .Lres_23
	s_cmp_lt_u32 s6, 2
	s_cbranch_scc0 .Lres_1
	v_mfma_f32_16x16x16_f16 v[126:129], v[198:199], v[236:237], v[126:129]
	v_mfma_f32_16x16x16_f16 v[122:125], v[198:199], v[238:239], v[122:125]
	v_mfma_f32_16x16x16_f16 v[118:121], v[198:199], v[240:241], v[118:121]
	v_mfma_f32_16x16x16_f16 v[114:117], v[198:199], v[242:243], v[114:117]
	s_branch .Lres_done

; #define PG8_STAGE(bufoff, gbase) do { _Pragma("unroll") for (int _i = 0; _i < 2; ++_i) \
;         __builtin_amdgcn_global_load_lds((const unsigned*)((const char*)(gbase) + voffA[_i]), (LAS unsigned*)(lds + (bufoff) + ldsw + _i * 8192), 16, 0, 0); } while (0)
; #define PG8_LDA(dst, b, h) do { _Pragma("unroll") for (int m = 0; m < 4; ++m) _Pragma("unroll") for (int k = 0; k < 2; ++k) dst[m][k] = *(const LAS f16x8*)(lds + PG8_SA(b, h) + aoff + m * 2048 + k * 1024); } while (0)
; #define PG8_MMA(ai, bj, At, Bt) do { __builtin_amdgcn_s_setprio(1); _Pragma("unroll") for (int m = 0; m < 4; ++m) _Pragma("unroll") for (int n = 0; n < 2; ++n) _Pragma("unroll") for (int k = 0; k < 2; ++k) \
;         acc[ai][bj][m][n] = __builtin_amdgcn_mfma_f32_16x16x32_f16(Bt[n][k], At[m][k], acc[ai][bj][m][n], 0, 0, 0); __builtin_amdgcn_s_setprio(0); } while (0)
; #define PG8_WAIT_V(n) asm volatile("s_waitcnt vmcnt(" #n ")" ::: "memory")
; #define PG8_WAIT_L(n) asm volatile("s_waitcnt lgkmcnt(" #n ")" ::: "memory")
; #define PG8_BAR __builtin_amdgcn_s_barrier()
; #define PG8_SCHED __builtin_amdgcn_sched_barrier(0)
; template <class Epi, bool SPLITA>
; __device__ __forceinline__ void gemm_phase(LAS unsigned char* lds, const Gemm g, const StaticOrder& S, const Epi& E) {
;     ...
;             PG8_LDA(At, 1, 1); PG8_STAGE(PG8_SB(1, 0), b3); PG8_STAGE(PG8_SB(1, 1), b3 + hstep); PG8_STAGE_A(PG8_SA(1, 0), pm2, kt2 + 1, 0);
;             PG8_WAIT_V(8); PG8_WAIT_L(0); PG8_BAR; PG8_MMA(1, 0, At, B0); PG8_MMA(1, 1, At, B1); PG8_BAR; PG8_SCHED;
.Lres_done:
	s_barrier
	s_mov_b32 m0, s53
	v_lshl_add_u64 v[196:197], v[210:211], 0, s[88:89]
	s_add_u32 s78, s78, 0x40080
	ds_read_b128 v[186:189], v233 offset:49152
	ds_read_b128 v[190:193], v233 offset:50176
	ds_read_b128 v[178:181], v233 offset:51200
	ds_read_b128 v[182:185], v233 offset:52224
	ds_read_b128 v[170:173], v233 offset:53248
	ds_read_b128 v[174:177], v233 offset:54272
	ds_read_b128 v[162:165], v233 offset:55296
	ds_read_b128 v[166:169], v233 offset:56320
	global_load_lds_dwordx4 v[196:197], off
	v_lshl_add_u64 v[196:197], v[212:213], 0, s[88:89]
	s_mov_b32 m0, s64
	s_addc_u32 s79, s79, 0
	global_load_lds_dwordx4 v[196:197], off
	v_lshl_add_u64 v[196:197], s[78:79], 0, v[194:195]
	s_mov_b32 m0, s86
	s_mov_b64 s[82:83], -1
	global_load_lds_dwordx4 v[196:197], off
	v_lshl_add_u64 v[196:197], s[78:79], 0, v[202:203]
	s_mov_b32 m0, s87
	s_and_b64 vcc, exec, s[80:81]
	global_load_lds_dwordx4 v[196:197], off
	s_cbranch_vccz .LBB0_496
	s_ashr_i32 s77, s76, 31
	s_lshl_b64 s[78:79], s[76:77], 18
	s_add_u32 s67, s62, s78
	s_addc_u32 s77, s63, s79
	s_lshl_b32 s78, s66, 7
	s_add_u32 s67, s67, s78
	s_addc_u32 s77, s77, 0
	s_add_u32 s78, s67, 0x80
	s_addc_u32 s79, s77, 0
	s_mov_b64 s[82:83], 0

; #define PG8_WAIT_V(n) asm volatile("s_waitcnt vmcnt(" #n ")" ::: "memory")
; #define PG8_BAR __builtin_amdgcn_s_barrier()
; template <class Epi, bool SPLITA>
; __device__ __forceinline__ void gemm_phase(LAS unsigned char* lds, const Gemm g, const StaticOrder& S, const Epi& E) {
;     ...
;     PG8_WAIT_V(0);
;     PG8_BAR;
.LBB0_507:
	s_setprio 0
	s_waitcnt vmcnt(0)
	v_readlane_b32 s82, v254, 55
	v_readlane_b32 s86, v254, 57
	v_readlane_b32 s90, v254, 60
	v_readlane_b32 s92, v254, 62
	v_readlane_b32 s94, v255, 0
	v_readlane_b32 s4, v255, 6
	v_readlane_b32 s6, v255, 2
	v_readlane_b32 s83, v254, 56
	v_readlane_b32 s87, v254, 58
	v_readlane_b32 s85, v254, 59
	v_readlane_b32 s91, v254, 61
	v_readlane_b32 s93, v254, 63
	v_readlane_b32 s95, v255, 1
	v_readlane_b32 s5, v255, 7
	v_readlane_b32 s7, v255, 3
	s_barrier
